# v19 with the MLA in-stream K/V staging moved to the last MFMA gaps (loads get a full iteration to land)
# speedup vs baseline: 1.0034x; 1.0034x over previous
.LBB0_451:
	v_exp_f32_e32 v64, v64
	v_exp_f32_e32 v65, v65
	v_exp_f32_e32 v66, v66
	s_waitcnt lgkmcnt(10)
	v_mfma_f32_32x32x16_bf16 v[80:95], v[212:215], v[120:123], v[80:95]
	ds_read_b128 v[208:211], v200 offset:32768
	v_exp_f32_e32 v67, v67
	v_exp_f32_e32 v68, v68
	v_exp_f32_e32 v69, v69
	s_waitcnt lgkmcnt(10)
	v_mfma_f32_32x32x16_bf16 v[96:111], v[216:219], v[124:127], v[96:111]
	ds_read_b128 v[212:215], v200 offset:36864
	v_exp_f32_e32 v70, v70
	v_exp_f32_e32 v71, v71
	v_cvt_pk_bf16_f32 v224, v64, v65
	v_cvt_pk_bf16_f32 v225, v66, v67
	s_waitcnt lgkmcnt(10)
	v_mfma_f32_32x32x16_bf16 v[80:95], v[220:223], v[124:127], v[80:95]
	ds_read_b128 v[216:219], v201 offset:32768
	v_cvt_pk_bf16_f32 v226, v68, v69
	v_cvt_pk_bf16_f32 v227, v70, v71
	v_exp_f32_e32 v72, v72
	v_exp_f32_e32 v73, v73
	s_waitcnt lgkmcnt(4)
	v_mfma_f32_32x32x16_bf16 v[32:47], v[174:177], v[224:227], v[32:47]
	ds_read_b128 v[220:223], v201 offset:36864
	v_exp_f32_e32 v74, v74
	v_exp_f32_e32 v75, v75
	v_exp_f32_e32 v76, v76
	s_waitcnt lgkmcnt(4)
	v_mfma_f32_32x32x16_bf16 v[16:31], v[204:207], v[224:227], v[16:31]
	v_exp_f32_e32 v77, v77
	v_exp_f32_e32 v78, v78
	v_exp_f32_e32 v79, v79
	v_mfma_f32_32x32x16_bf16 v[96:111], v[230:233], v[128:131], v[96:111]
	v_cvt_pk_bf16_f32 v224, v72, v73
	v_cvt_pk_bf16_f32 v225, v74, v75
	v_cvt_pk_bf16_f32 v226, v76, v77
	v_cvt_pk_bf16_f32 v227, v78, v79
	v_exp_f32_e32 v48, v48
	v_mfma_f32_32x32x16_bf16 v[80:95], v[234:237], v[128:131], v[80:95]
	ds_read_b128 v[230:233], v202 offset:32768
	v_exp_f32_e32 v49, v49
	v_exp_f32_e32 v50, v50
	v_exp_f32_e32 v51, v51
	s_waitcnt lgkmcnt(4)
	v_mfma_f32_32x32x16_bf16 v[32:47], v[208:211], v[224:227], v[32:47]
	ds_read_b128 v[234:237], v202 offset:36864
	v_exp_f32_e32 v52, v52
	v_exp_f32_e32 v53, v53
	v_exp_f32_e32 v54, v54
	s_waitcnt lgkmcnt(4)
	v_mfma_f32_32x32x16_bf16 v[16:31], v[212:215], v[224:227], v[16:31]
	v_exp_f32_e32 v55, v55
	v_cvt_pk_bf16_f32 v224, v48, v49
	v_cvt_pk_bf16_f32 v225, v50, v51
	v_cvt_pk_bf16_f32 v226, v52, v53
	v_cvt_pk_bf16_f32 v227, v54, v55
	v_mfma_f32_32x32x16_bf16 v[96:111], v[238:241], v[132:135], v[96:111]
	v_exp_f32_e32 v56, v56
	v_exp_f32_e32 v57, v57
	v_exp_f32_e32 v58, v58
	v_mfma_f32_32x32x16_bf16 v[80:95], v[242:245], v[132:135], v[80:95]
	v_exp_f32_e32 v59, v59
	v_exp_f32_e32 v60, v60
	v_exp_f32_e32 v61, v61
	s_waitcnt lgkmcnt(3)
	v_mfma_f32_32x32x16_bf16 v[32:47], v[216:219], v[224:227], v[32:47]
	v_exp_f32_e32 v62, v62
	v_exp_f32_e32 v63, v63
	v_pk_add_f32 v[64:65], v[48:49], v[64:65]
	s_waitcnt lgkmcnt(2)
	v_mfma_f32_32x32x16_bf16 v[16:31], v[220:223], v[224:227], v[16:31]
	v_cvt_pk_bf16_f32 v224, v56, v57
	v_cvt_pk_bf16_f32 v225, v58, v59
	v_cvt_pk_bf16_f32 v226, v60, v61
	v_cvt_pk_bf16_f32 v227, v62, v63
	v_pk_add_f32 v[66:67], v[50:51], v[66:67]
	v_mfma_f32_32x32x16_bf16 v[96:111], v[246:249], v[136:139], v[96:111]
	v_pk_add_f32 v[68:69], v[52:53], v[68:69]
	v_pk_add_f32 v[70:71], v[54:55], v[70:71]
	v_pk_add_f32 v[72:73], v[56:57], v[72:73]
	s_add_i32 s98, s73, 2
	s_cmp_ge_u32 s98, s70
	s_cbranch_scc1 .Lst_noK
	s_lshl_b32 s99, s68, 14
	v_add_u32_e32 v176, s99, v188
	s_waitcnt vmcnt(0)
	ds_write_b128 v176, v[144:147]
	s_and_saveexec_b64 s[100:101], s[6:7]
	v_add_u32_e32 v176, s99, v189
	ds_write_b128 v176, v[140:143]
	s_or_b64 exec, exec, s[100:101]
	s_nop 3
.Lst_noK:
	v_mfma_f32_32x32x16_bf16 v[80:95], v[250:253], v[136:139], v[80:95]
	v_pk_add_f32 v[74:75], v[58:59], v[74:75]
	v_pk_add_f32 v[76:77], v[60:61], v[76:77]
	v_pk_add_f32 v[78:79], v[62:63], v[78:79]
	s_and_b32 s99, s71, 0x2000
	v_add_u32_e32 v176, s99, v192
	v_add_u32_e32 v177, s99, v193
	s_waitcnt vmcnt(0)
	ds_write_b64 v176, v[148:149] offset:32768
	ds_write_b64 v177, v[150:151]
	s_waitcnt lgkmcnt(3)
	v_mfma_f32_32x32x16_bf16 v[32:47], v[230:233], v[224:227], v[32:47]
	v_pk_add_f32 v[0:1], v[64:65], v[0:1]
	v_pk_add_f32 v[2:3], v[66:67], v[2:3]
	v_pk_add_f32 v[4:5], v[68:69], v[4:5]
	s_add_i32 s99, s73, 3
	s_cmp_ge_u32 s99, s70
	s_cbranch_scc1 .Lst_noKL
	s_lshl_b64 s[100:101], s[14:15], 11
	v_lshl_add_u64 v[174:175], v[166:167], 0, s[100:101]
	global_load_dwordx4 v[144:147], v[174:175], off
	s_and_saveexec_b64 s[100:101], s[6:7]
	s_cbranch_execz .Lst_noR
	s_lshl_b64 s[78:79], s[14:15], 6
	v_lshl_add_u64 v[174:175], v[164:165], 0, s[78:79]
	global_load_dwordx4 v[140:143], v[174:175], off

.Lst_noKL:
	s_waitcnt lgkmcnt(2)
	v_mfma_f32_32x32x16_bf16 v[16:31], v[234:237], v[224:227], v[16:31]
	v_cmp_neq_f32_e32 vcc, 0, v229
	v_pk_add_f32 v[6:7], v[70:71], v[6:7]
	v_pk_add_f32 v[8:9], v[72:73], v[8:9]
	v_pk_add_f32 v[10:11], v[74:75], v[10:11]
	v_pk_add_f32 v[12:13], v[76:77], v[12:13]
	v_pk_add_f32 v[14:15], v[78:79], v[14:15]
	s_cmp_ge_u32 s98, s70
	s_cbranch_scc1 .Lst_noVL
	s_sub_i32 s100, s14, 64
	s_mov_b32 s101, s15
	v_lshl_add_u64 v[174:175], s[100:101], 1, v[168:169]
	global_load_dwordx4 v[148:151], v[174:175], off
.Lst_noVL:
	s_mov_b32 s98, 1
	s_cbranch_vccz .LBB0_453
	v_sub_f32_e32 v111, v111, v229
	v_sub_f32_e32 v110, v110, v229
	v_sub_f32_e32 v109, v109, v229
	v_sub_f32_e32 v108, v108, v229
	v_sub_f32_e32 v107, v107, v229
	v_sub_f32_e32 v106, v106, v229
	v_sub_f32_e32 v105, v105, v229
	v_sub_f32_e32 v104, v104, v229
	v_sub_f32_e32 v103, v103, v229
	v_sub_f32_e32 v102, v102, v229
	v_sub_f32_e32 v101, v101, v229
	v_sub_f32_e32 v100, v100, v229
	v_sub_f32_e32 v99, v99, v229
	v_sub_f32_e32 v98, v98, v229
	v_sub_f32_e32 v97, v97, v229
	v_sub_f32_e32 v96, v96, v229
	v_sub_f32_e32 v95, v95, v229
	v_sub_f32_e32 v94, v94, v229
	v_sub_f32_e32 v93, v93, v229
	v_sub_f32_e32 v92, v92, v229
	v_sub_f32_e32 v91, v91, v229
	v_sub_f32_e32 v90, v90, v229
	v_sub_f32_e32 v89, v89, v229
	v_sub_f32_e32 v88, v88, v229
	v_sub_f32_e32 v87, v87, v229
	v_sub_f32_e32 v86, v86, v229
	v_sub_f32_e32 v85, v85, v229
	v_sub_f32_e32 v84, v84, v229
	v_sub_f32_e32 v83, v83, v229
	v_sub_f32_e32 v82, v82, v229
	v_sub_f32_e32 v81, v81, v229
	v_sub_f32_e32 v80, v80, v229

.Lmo_451:
	v_exp_f32_e32 v96, v96
	v_exp_f32_e32 v97, v97
	v_exp_f32_e32 v98, v98
	s_waitcnt lgkmcnt(10)
	v_mfma_f32_32x32x16_bf16 v[48:63], v[212:215], v[120:123], v[48:63]
	ds_read_b128 v[208:211], v200 offset:40960
	v_exp_f32_e32 v99, v99
	v_exp_f32_e32 v100, v100
	v_exp_f32_e32 v101, v101
	s_waitcnt lgkmcnt(10)
	v_mfma_f32_32x32x16_bf16 v[64:79], v[216:219], v[124:127], v[64:79]
	ds_read_b128 v[212:215], v200 offset:45056
	v_exp_f32_e32 v102, v102
	v_exp_f32_e32 v103, v103
	v_cvt_pk_bf16_f32 v224, v96, v97
	v_cvt_pk_bf16_f32 v225, v98, v99
	s_waitcnt lgkmcnt(10)
	v_mfma_f32_32x32x16_bf16 v[48:63], v[220:223], v[124:127], v[48:63]
	ds_read_b128 v[216:219], v201 offset:40960
	v_cvt_pk_bf16_f32 v226, v100, v101
	v_cvt_pk_bf16_f32 v227, v102, v103
	v_exp_f32_e32 v104, v104
	v_exp_f32_e32 v105, v105
	s_waitcnt lgkmcnt(4)
	v_mfma_f32_32x32x16_bf16 v[32:47], v[174:177], v[224:227], v[32:47]
	ds_read_b128 v[220:223], v201 offset:45056
	v_exp_f32_e32 v106, v106
	v_exp_f32_e32 v107, v107
	v_exp_f32_e32 v108, v108
	s_waitcnt lgkmcnt(4)
	v_mfma_f32_32x32x16_bf16 v[16:31], v[204:207], v[224:227], v[16:31]
	v_exp_f32_e32 v109, v109
	v_exp_f32_e32 v110, v110
	v_exp_f32_e32 v111, v111
	v_mfma_f32_32x32x16_bf16 v[64:79], v[230:233], v[128:131], v[64:79]
	v_cvt_pk_bf16_f32 v224, v104, v105
	v_cvt_pk_bf16_f32 v225, v106, v107
	v_cvt_pk_bf16_f32 v226, v108, v109
	v_cvt_pk_bf16_f32 v227, v110, v111
	v_exp_f32_e32 v80, v80
	v_mfma_f32_32x32x16_bf16 v[48:63], v[234:237], v[128:131], v[48:63]
	ds_read_b128 v[230:233], v202 offset:40960
	v_exp_f32_e32 v81, v81
	v_exp_f32_e32 v82, v82
	v_exp_f32_e32 v83, v83
	s_waitcnt lgkmcnt(4)
	v_mfma_f32_32x32x16_bf16 v[32:47], v[208:211], v[224:227], v[32:47]
	ds_read_b128 v[234:237], v202 offset:45056
	v_exp_f32_e32 v84, v84
	v_exp_f32_e32 v85, v85
	v_exp_f32_e32 v86, v86
	s_waitcnt lgkmcnt(4)
	v_mfma_f32_32x32x16_bf16 v[16:31], v[212:215], v[224:227], v[16:31]
	v_exp_f32_e32 v87, v87
	v_cvt_pk_bf16_f32 v224, v80, v81
	v_cvt_pk_bf16_f32 v225, v82, v83
	v_cvt_pk_bf16_f32 v226, v84, v85
	v_cvt_pk_bf16_f32 v227, v86, v87
	v_mfma_f32_32x32x16_bf16 v[64:79], v[238:241], v[132:135], v[64:79]
	v_exp_f32_e32 v88, v88
	v_exp_f32_e32 v89, v89
	v_exp_f32_e32 v90, v90
	v_mfma_f32_32x32x16_bf16 v[48:63], v[242:245], v[132:135], v[48:63]
	v_exp_f32_e32 v91, v91
	v_exp_f32_e32 v92, v92
	v_exp_f32_e32 v93, v93
	s_waitcnt lgkmcnt(3)
	v_mfma_f32_32x32x16_bf16 v[32:47], v[216:219], v[224:227], v[32:47]
	v_exp_f32_e32 v94, v94
	v_exp_f32_e32 v95, v95
	v_pk_add_f32 v[96:97], v[80:81], v[96:97]
	s_waitcnt lgkmcnt(2)
	v_mfma_f32_32x32x16_bf16 v[16:31], v[220:223], v[224:227], v[16:31]
	v_cvt_pk_bf16_f32 v224, v88, v89
	v_cvt_pk_bf16_f32 v225, v90, v91
	v_cvt_pk_bf16_f32 v226, v92, v93
	v_cvt_pk_bf16_f32 v227, v94, v95
	v_pk_add_f32 v[98:99], v[82:83], v[98:99]
	v_mfma_f32_32x32x16_bf16 v[64:79], v[246:249], v[136:139], v[64:79]
	v_pk_add_f32 v[100:101], v[84:85], v[100:101]
	v_pk_add_f32 v[102:103], v[86:87], v[102:103]
	v_pk_add_f32 v[104:105], v[88:89], v[104:105]
	s_add_i32 s98, s73, 2
	s_cmp_ge_u32 s98, s70
	s_cbranch_scc1 .Lsto_noK
	s_lshl_b32 s99, s68, 14
	v_add_u32_e32 v176, s99, v188
	s_waitcnt vmcnt(0)
	ds_write_b128 v176, v[144:147]
	s_and_saveexec_b64 s[100:101], s[6:7]
	v_add_u32_e32 v176, s99, v189
	ds_write_b128 v176, v[140:143]
	s_or_b64 exec, exec, s[100:101]
	s_nop 3
.Lsto_noK:
	v_mfma_f32_32x32x16_bf16 v[48:63], v[250:253], v[136:139], v[48:63]
	v_pk_add_f32 v[106:107], v[90:91], v[106:107]
	v_pk_add_f32 v[108:109], v[92:93], v[108:109]
	v_pk_add_f32 v[110:111], v[94:95], v[110:111]
	s_and_b32 s99, s71, 0x2000
	v_add_u32_e32 v176, s99, v192
	v_add_u32_e32 v177, s99, v193
	s_waitcnt vmcnt(0)
	ds_write_b64 v176, v[148:149] offset:32768
	ds_write_b64 v177, v[150:151]
	s_waitcnt lgkmcnt(3)
	v_mfma_f32_32x32x16_bf16 v[32:47], v[230:233], v[224:227], v[32:47]
	v_pk_add_f32 v[0:1], v[96:97], v[0:1]
	v_pk_add_f32 v[2:3], v[98:99], v[2:3]
	v_pk_add_f32 v[4:5], v[100:101], v[4:5]
	s_add_i32 s99, s73, 3
	s_cmp_ge_u32 s99, s70
	s_cbranch_scc1 .Lsto_noKL
	s_lshl_b64 s[100:101], s[14:15], 11
	v_lshl_add_u64 v[174:175], v[166:167], 0, s[100:101]
	global_load_dwordx4 v[144:147], v[174:175], off
	s_and_saveexec_b64 s[100:101], s[6:7]
	s_cbranch_execz .Lsto_noR
	s_lshl_b64 s[78:79], s[14:15], 6
	v_lshl_add_u64 v[174:175], v[164:165], 0, s[78:79]
	global_load_dwordx4 v[140:143], v[174:175], off

.Lsto_noKL:
	s_waitcnt lgkmcnt(2)
	v_mfma_f32_32x32x16_bf16 v[16:31], v[234:237], v[224:227], v[16:31]
	v_cmp_neq_f32_e32 vcc, 0, v229
	v_pk_add_f32 v[6:7], v[102:103], v[6:7]
	v_pk_add_f32 v[8:9], v[104:105], v[8:9]
	v_pk_add_f32 v[10:11], v[106:107], v[10:11]
	v_pk_add_f32 v[12:13], v[108:109], v[12:13]
	v_pk_add_f32 v[14:15], v[110:111], v[14:15]
	s_cmp_ge_u32 s98, s70
	s_cbranch_scc1 .Lsto_noVL
	s_sub_i32 s100, s14, 64
	s_mov_b32 s101, s15
	v_lshl_add_u64 v[174:175], s[100:101], 1, v[168:169]
	global_load_dwordx4 v[148:151], v[174:175], off
.Lsto_noVL:
	s_mov_b32 s98, 1
	s_cbranch_vccz .Lmo_453
	v_sub_f32_e32 v79, v79, v229
	v_sub_f32_e32 v78, v78, v229
	v_sub_f32_e32 v77, v77, v229
	v_sub_f32_e32 v76, v76, v229
	v_sub_f32_e32 v75, v75, v229
	v_sub_f32_e32 v74, v74, v229
	v_sub_f32_e32 v73, v73, v229
	v_sub_f32_e32 v72, v72, v229
	v_sub_f32_e32 v71, v71, v229
	v_sub_f32_e32 v70, v70, v229
	v_sub_f32_e32 v69, v69, v229
	v_sub_f32_e32 v68, v68, v229
	v_sub_f32_e32 v67, v67, v229
	v_sub_f32_e32 v66, v66, v229
	v_sub_f32_e32 v65, v65, v229
	v_sub_f32_e32 v64, v64, v229
	v_sub_f32_e32 v63, v63, v229
	v_sub_f32_e32 v62, v62, v229
	v_sub_f32_e32 v61, v61, v229
	v_sub_f32_e32 v60, v60, v229
	v_sub_f32_e32 v59, v59, v229
	v_sub_f32_e32 v58, v58, v229
	v_sub_f32_e32 v57, v57, v229
	v_sub_f32_e32 v56, v56, v229
	v_sub_f32_e32 v55, v55, v229
	v_sub_f32_e32 v54, v54, v229
	v_sub_f32_e32 v53, v53, v229
	v_sub_f32_e32 v52, v52, v229
	v_sub_f32_e32 v51, v51, v229
	v_sub_f32_e32 v50, v50, v229
	v_sub_f32_e32 v49, v49, v229
	v_sub_f32_e32 v48, v48, v229
